# layer-1 weight transposes moved into the layer-0 out-projection phase: XCDs 0-3 before their first tile, XCDs 4-7 after their last, so the two halves' HBM-bound tile epilogues never coincide
# baseline (speedup 1.0000x reference)
.Ldt0_nrot:
	s_addk_i32 s52, 0xa08
	s_mul_i32 s9, s84, 10
	s_add_u32 s52, s52, s9
	s_mul_i32 s9, s84, 15
	s_addk_i32 s9, 0xa08
	s_min_u32 s9, s9, 0x1c10
	s_cmp_ge_u32 s52, s9
	s_cbranch_scc1 .Ldt0_skip
	s_waitcnt lgkmcnt(0)
	s_barrier
	v_readlane_b32 s54, v254, 54
	v_readlane_b32 s55, v254, 55
	v_readlane_b32 s56, v253, 2
	v_readlane_b32 s57, v253, 3
	v_readlane_b32 s58, v253, 8
	v_readlane_b32 s59, v253, 9
	v_readlane_b32 s60, v253, 10
	v_readlane_b32 s61, v253, 11
	v_readlane_b32 s62, v254, 12
	v_readlane_b32 s63, v254, 13
	v_and_b32_e32 v106, 7, v180
	v_lshrrev_b32_e32 v93, 3, v180
	s_add_u32 s54, s54, 0xa080000
	s_addc_u32 s55, s55, 0
	s_add_u32 s58, s58, 0x5000000
	s_addc_u32 s59, s59, 0
	s_add_u32 s60, s60, 0x40000
	s_addc_u32 s61, s61, 0
	v_lshlrev_b32_e32 v94, 4, v106
	v_bfe_u32 v107, v180, 3, 1
	v_lshlrev_b32_e32 v108, 2, v106
	v_lshl_add_u32 v108, v107, 1, v108
	v_mul_u32_u24_e32 v84, 0x410, v108
	v_lshrrev_b32_e32 v109, 3, v93
	v_xor_b32_e32 v109, v109, v106
	v_lshlrev_b32_e32 v109, 3, v109
	v_and_b32_e32 v110, 6, v93
	v_or_b32_e32 v109, v109, v110
	v_lshl_add_u32 v84, v109, 1, v84
	v_cmp_ne_u32_e64 s[74:75], 0, v107
	v_mov_b32_e32 v104, 0x1000504
	v_mov_b32_e32 v105, 0x3020706
	v_mov_b32_e32 v111, 0x5040100
	v_mov_b32_e32 v112, 0x7060302
	v_cndmask_b32_e64 v104, v104, v111, s[74:75]
	v_cndmask_b32_e64 v105, v105, v112, s[74:75]
	v_lshrrev_b32_e32 v106, 6, v180
	v_and_b32_e32 v107, 63, v180
	v_lshrrev_b32_e32 v108, 2, v106
	v_add_u32_e32 v109, 0, v108
	v_xor_b32_e32 v109, v109, v107
	v_lshlrev_b32_e32 v109, 4, v109
	v_add_u32_e32 v110, 0, v106
	v_mul_u32_u24_e32 v110, 0x410, v110
	v_add_u32_e32 v85, v109, v110
	v_add_u32_e32 v109, 2, v108
	v_xor_b32_e32 v109, v109, v107
	v_lshlrev_b32_e32 v109, 4, v109
	v_add_u32_e32 v110, 8, v106
	v_mul_u32_u24_e32 v110, 0x410, v110
	v_add_u32_e32 v86, v109, v110
	v_add_u32_e32 v109, 4, v108
	v_xor_b32_e32 v109, v109, v107
	v_lshlrev_b32_e32 v109, 4, v109
	v_add_u32_e32 v110, 16, v106
	v_mul_u32_u24_e32 v110, 0x410, v110
	v_add_u32_e32 v87, v109, v110
	v_add_u32_e32 v109, 6, v108
	v_xor_b32_e32 v109, v109, v107
	v_lshlrev_b32_e32 v109, 4, v109
	v_add_u32_e32 v110, 24, v106
	v_mul_u32_u24_e32 v110, 0x410, v110
	v_add_u32_e32 v88, v109, v110
	v_lshlrev_b32_e32 v109, 13, v106
	v_lshl_add_u32 v89, v107, 4, v109
	v_add_u32_e32 v90, 0x10000, v89
	v_add_u32_e32 v91, 0x20000, v89
	v_add_u32_e32 v92, 0x30000, v89
	s_mov_b32 s53, 0
	s_mov_b32 s73, 0
	s_cmpk_ge_u32 s52, 0x1410
	s_cbranch_scc1 .Ldt0_out0
	s_sub_i32 s0, s52, 0xa08
	s_mul_i32 s1, s0, 0xcc3
	s_lshr_b32 s1, s1, 20
	s_mul_i32 s2, s1, 0x141
	s_sub_u32 s2, s0, s2
	s_lshl_b32 s3, s2, 7
	s_mul_i32 s4, s1, 0x1410000
	s_add_u32 s3, s3, s4
	s_add_u32 s64, s54, s3
	s_addc_u32 s65, s55, 0
	s_mov_b32 s7, 0xa080
	s_lshl_b32 s4, s1, 10
	s_cmpk_lt_u32 s2, 0x80
	s_cbranch_scc1 .Ldt0_wlo0
	s_cmpk_eq_u32 s2, 0x80
	s_cbranch_scc1 .Ldt0_wlr0
	s_add_i32 s2, s2, -1

.LBB0_805:
	s_bitcmp1_b32 s96, 2
	s_cbranch_scc1 .Ldt5_skip
	s_cmp_lg_u32 s56, s96
	s_cbranch_scc1 .Ldt5_skip
	s_mov_b32 s57, s96
	s_cmpk_lg_u32 s94, 0x100
	s_cbranch_scc1 .Ldt5_nrot
	s_xor_b32 s57, s57, 0x80

.Ldt5_nlA:
	ds_write_b32 v84, v68 offset:0
	ds_write_b32 v84, v69 offset:1040
	ds_write_b32 v84, v70 offset:128
	ds_write_b32 v84, v71 offset:1168
	ds_write_b32 v84, v72 offset:256
	ds_write_b32 v84, v73 offset:1296
	ds_write_b32 v84, v74 offset:384
	ds_write_b32 v84, v75 offset:1424
	ds_write_b32 v84, v76 offset:512
	ds_write_b32 v84, v77 offset:1552
	ds_write_b32 v84, v78 offset:640
	ds_write_b32 v84, v79 offset:1680
	ds_write_b32 v84, v80 offset:768
	ds_write_b32 v84, v81 offset:1808
	ds_write_b32 v84, v82 offset:896
	ds_write_b32 v84, v83 offset:1936
	s_waitcnt lgkmcnt(0)
	s_barrier
	ds_read_b128 v[68:71], v85 offset:0
	ds_read_b128 v[72:75], v86 offset:0
	ds_read_b128 v[76:79], v87 offset:0
	ds_read_b128 v[80:83], v88 offset:0
	s_waitcnt lgkmcnt(3)
	global_store_dwordx4 v89, v[68:71], s[76:77] nt
	s_waitcnt lgkmcnt(2)
	global_store_dwordx4 v90, v[72:75], s[76:77] nt
	s_waitcnt lgkmcnt(1)
	global_store_dwordx4 v91, v[76:79], s[76:77] nt
	s_waitcnt lgkmcnt(0)
	global_store_dwordx4 v92, v[80:83], s[76:77] nt
	s_add_u32 s58, s58, 1
	s_cmp_eq_u32 s79, 0
	s_cbranch_scc1 .Ldt5_end

.Ldt5_nlB:
	ds_write_b32 v84, v68 offset:33280
	ds_write_b32 v84, v69 offset:34320
	ds_write_b32 v84, v70 offset:33408
	ds_write_b32 v84, v71 offset:34448
	ds_write_b32 v84, v72 offset:33536
	ds_write_b32 v84, v73 offset:34576
	ds_write_b32 v84, v74 offset:33664
	ds_write_b32 v84, v75 offset:34704
	ds_write_b32 v84, v76 offset:33792
	ds_write_b32 v84, v77 offset:34832
	ds_write_b32 v84, v78 offset:33920
	ds_write_b32 v84, v79 offset:34960
	ds_write_b32 v84, v80 offset:34048
	ds_write_b32 v84, v81 offset:35088
	ds_write_b32 v84, v82 offset:34176
	ds_write_b32 v84, v83 offset:35216
	s_waitcnt lgkmcnt(0)
	s_barrier
	ds_read_b128 v[68:71], v85 offset:33280
	ds_read_b128 v[72:75], v86 offset:33280
	ds_read_b128 v[76:79], v87 offset:33280
	ds_read_b128 v[80:83], v88 offset:33280
	s_waitcnt lgkmcnt(3)
	global_store_dwordx4 v89, v[68:71], s[76:77] nt
	s_waitcnt lgkmcnt(2)
	global_store_dwordx4 v90, v[72:75], s[76:77] nt
	s_waitcnt lgkmcnt(1)
	global_store_dwordx4 v91, v[76:79], s[76:77] nt
	s_waitcnt lgkmcnt(0)
	global_store_dwordx4 v92, v[80:83], s[76:77] nt
	s_add_u32 s58, s58, 1
	s_cmp_eq_u32 s78, 0
	s_cbranch_scc0 .Ldt5_procA

.Ldt6_nrot:
	s_addk_i32 s57, 0xa08
	s_mul_i32 s32, s94, 15
	s_add_u32 s57, s57, s32
	s_movk_i32 s32, 0x1c10
	s_cmp_ge_u32 s57, s32
	s_cbranch_scc1 .Ldt6_skip
	s_waitcnt lgkmcnt(0)
	s_barrier
	v_readlane_b32 s60, v254, 54
	v_readlane_b32 s61, v254, 55
	v_readlane_b32 s62, v253, 2
	v_readlane_b32 s63, v253, 3
	v_readlane_b32 s64, v253, 8
	v_readlane_b32 s65, v253, 9
	v_readlane_b32 s66, v253, 10
	v_readlane_b32 s67, v253, 11
	v_readlane_b32 s68, v254, 12
	v_readlane_b32 s69, v254, 13
	v_and_b32_e32 v106, 7, v180
	v_lshrrev_b32_e32 v93, 3, v180
	s_add_u32 s60, s60, 0xa080000
	s_addc_u32 s61, s61, 0
	s_add_u32 s64, s64, 0x5000000
	s_addc_u32 s65, s65, 0
	s_add_u32 s66, s66, 0x40000
	s_addc_u32 s67, s67, 0
	v_lshlrev_b32_e32 v94, 4, v106
	v_bfe_u32 v107, v180, 3, 1
	v_lshlrev_b32_e32 v108, 2, v106
	v_lshl_add_u32 v108, v107, 1, v108
	v_mul_u32_u24_e32 v84, 0x410, v108
	v_lshrrev_b32_e32 v109, 3, v93
	v_xor_b32_e32 v109, v109, v106
	v_lshlrev_b32_e32 v109, 3, v109
	v_and_b32_e32 v110, 6, v93
	v_or_b32_e32 v109, v109, v110
	v_lshl_add_u32 v84, v109, 1, v84
	v_cmp_ne_u32_e64 s[80:81], 0, v107
	v_mov_b32_e32 v104, 0x1000504
	v_mov_b32_e32 v105, 0x3020706
	v_mov_b32_e32 v111, 0x5040100
	v_mov_b32_e32 v112, 0x7060302
	v_cndmask_b32_e64 v104, v104, v111, s[80:81]
	v_cndmask_b32_e64 v105, v105, v112, s[80:81]
	v_lshrrev_b32_e32 v106, 6, v180
	v_and_b32_e32 v107, 63, v180
	v_lshrrev_b32_e32 v108, 2, v106
	v_add_u32_e32 v109, 0, v108
	v_xor_b32_e32 v109, v109, v107
	v_lshlrev_b32_e32 v109, 4, v109
	v_add_u32_e32 v110, 0, v106
	v_mul_u32_u24_e32 v110, 0x410, v110
	v_add_u32_e32 v85, v109, v110
	v_add_u32_e32 v109, 2, v108
	v_xor_b32_e32 v109, v109, v107
	v_lshlrev_b32_e32 v109, 4, v109
	v_add_u32_e32 v110, 8, v106
	v_mul_u32_u24_e32 v110, 0x410, v110
	v_add_u32_e32 v86, v109, v110
	v_add_u32_e32 v109, 4, v108
	v_xor_b32_e32 v109, v109, v107
	v_lshlrev_b32_e32 v109, 4, v109
	v_add_u32_e32 v110, 16, v106
	v_mul_u32_u24_e32 v110, 0x410, v110
	v_add_u32_e32 v87, v109, v110
	v_add_u32_e32 v109, 6, v108
	v_xor_b32_e32 v109, v109, v107
	v_lshlrev_b32_e32 v109, 4, v109
	v_add_u32_e32 v110, 24, v106
	v_mul_u32_u24_e32 v110, 0x410, v110
	v_add_u32_e32 v88, v109, v110
	v_lshlrev_b32_e32 v109, 13, v106
	v_lshl_add_u32 v89, v107, 4, v109
	v_add_u32_e32 v90, 0x10000, v89
	v_add_u32_e32 v91, 0x20000, v89
	v_add_u32_e32 v92, 0x30000, v89
	s_mov_b32 s58, 0
	s_mov_b32 s79, 0
	s_cmpk_ge_u32 s57, 0x1410
	s_cbranch_scc1 .Ldt6_out0
	s_sub_i32 s0, s57, 0xa08
	s_mul_i32 s2, s0, 0xcc3
	s_lshr_b32 s2, s2, 20
	s_mul_i32 s3, s2, 0x141
	s_sub_u32 s3, s0, s3
	s_lshl_b32 s17, s3, 7
	s_mul_i32 s20, s2, 0x1410000
	s_add_u32 s17, s17, s20
	s_add_u32 s70, s60, s17
	s_addc_u32 s71, s61, 0
	s_mov_b32 s25, 0xa080
	s_lshl_b32 s20, s2, 10
	s_cmpk_lt_u32 s3, 0x80
	s_cbranch_scc1 .Ldt6_wlo0
	s_cmpk_eq_u32 s3, 0x80
	s_cbranch_scc1 .Ldt6_wlr0
	s_add_i32 s3, s3, -1

.LBB0_816:
	s_bitcmp0_b32 s96, 2
	s_cbranch_scc1 .Ldt7_skip
	s_mov_b32 s52, s96
	s_cmpk_lg_u32 s94, 0x100
	s_cbranch_scc1 .Ldt7_nrot
	s_xor_b32 s52, s52, 0x80
.Ldt7_nrot:
	s_addk_i32 s52, 0xa08
	s_mul_i32 s9, s94, 10
	s_addk_i32 s9, 0xa08
	s_min_u32 s9, s9, 0x1c10
	s_cmp_ge_u32 s52, s9
	s_cbranch_scc1 .Ldt7_skip
	s_waitcnt lgkmcnt(0)
	s_barrier
	v_readlane_b32 s54, v254, 54
	v_readlane_b32 s55, v254, 55
	v_readlane_b32 s56, v253, 2
	v_readlane_b32 s57, v253, 3
	v_readlane_b32 s58, v253, 8
	v_readlane_b32 s59, v253, 9
	v_readlane_b32 s60, v253, 10
	v_readlane_b32 s61, v253, 11
	v_readlane_b32 s62, v254, 12
	v_readlane_b32 s63, v254, 13
	v_and_b32_e32 v106, 7, v180
	v_lshrrev_b32_e32 v93, 3, v180
	s_add_u32 s54, s54, 0xa080000
	s_addc_u32 s55, s55, 0
	s_add_u32 s58, s58, 0x5000000
	s_addc_u32 s59, s59, 0
	s_add_u32 s60, s60, 0x40000
	s_addc_u32 s61, s61, 0
	v_lshlrev_b32_e32 v94, 4, v106
	v_bfe_u32 v107, v180, 3, 1
	v_lshlrev_b32_e32 v108, 2, v106
	v_lshl_add_u32 v108, v107, 1, v108
	v_mul_u32_u24_e32 v84, 0x410, v108
	v_lshrrev_b32_e32 v109, 3, v93
	v_xor_b32_e32 v109, v109, v106
	v_lshlrev_b32_e32 v109, 3, v109
	v_and_b32_e32 v110, 6, v93
	v_or_b32_e32 v109, v109, v110
	v_lshl_add_u32 v84, v109, 1, v84
	v_cmp_ne_u32_e64 s[74:75], 0, v107
	v_mov_b32_e32 v104, 0x1000504
	v_mov_b32_e32 v105, 0x3020706
	v_mov_b32_e32 v111, 0x5040100
	v_mov_b32_e32 v112, 0x7060302
	v_cndmask_b32_e64 v104, v104, v111, s[74:75]
	v_cndmask_b32_e64 v105, v105, v112, s[74:75]
	v_lshrrev_b32_e32 v106, 6, v180
	v_and_b32_e32 v107, 63, v180
	v_lshrrev_b32_e32 v108, 2, v106
	v_add_u32_e32 v109, 0, v108
	v_xor_b32_e32 v109, v109, v107
	v_lshlrev_b32_e32 v109, 4, v109
	v_add_u32_e32 v110, 0, v106
	v_mul_u32_u24_e32 v110, 0x410, v110
	v_add_u32_e32 v85, v109, v110
	v_add_u32_e32 v109, 2, v108
	v_xor_b32_e32 v109, v109, v107
	v_lshlrev_b32_e32 v109, 4, v109
	v_add_u32_e32 v110, 8, v106
	v_mul_u32_u24_e32 v110, 0x410, v110
	v_add_u32_e32 v86, v109, v110
	v_add_u32_e32 v109, 4, v108
	v_xor_b32_e32 v109, v109, v107
	v_lshlrev_b32_e32 v109, 4, v109
	v_add_u32_e32 v110, 16, v106
	v_mul_u32_u24_e32 v110, 0x410, v110
	v_add_u32_e32 v87, v109, v110
	v_add_u32_e32 v109, 6, v108
	v_xor_b32_e32 v109, v109, v107
	v_lshlrev_b32_e32 v109, 4, v109
	v_add_u32_e32 v110, 24, v106
	v_mul_u32_u24_e32 v110, 0x410, v110
	v_add_u32_e32 v88, v109, v110
	v_lshlrev_b32_e32 v109, 13, v106
	v_lshl_add_u32 v89, v107, 4, v109
	v_add_u32_e32 v90, 0x10000, v89
	v_add_u32_e32 v91, 0x20000, v89
	v_add_u32_e32 v92, 0x30000, v89
	s_mov_b32 s53, 0
	s_mov_b32 s73, 0
	s_cmpk_ge_u32 s52, 0x1410
	s_cbranch_scc1 .Ldt7_out0
	s_sub_i32 s0, s52, 0xa08
	s_mul_i32 s1, s0, 0xcc3
	s_lshr_b32 s1, s1, 20
	s_mul_i32 s2, s1, 0x141
	s_sub_u32 s2, s0, s2
	s_lshl_b32 s3, s2, 7
	s_mul_i32 s4, s1, 0x1410000
	s_add_u32 s3, s3, s4
	s_add_u32 s64, s54, s3
	s_addc_u32 s65, s55, 0
	s_mov_b32 s7, 0xa080
	s_lshl_b32 s4, s1, 10
	s_cmpk_lt_u32 s2, 0x80
	s_cbranch_scc1 .Ldt7_wlo0
	s_cmpk_eq_u32 s2, 0x80
	s_cbranch_scc1 .Ldt7_wlr0
	s_add_i32 s2, s2, -1

.Ldt7_ud0:
	v_mul_u32_u24_e32 v96, s7, v93
	s_lshl_b32 s6, s7, 6
	v_add_u32_e32 v96, v96, v94
	v_add_u32_e32 v97, s6, v96
	v_add_u32_e32 v98, s6, v97
	v_add_u32_e32 v99, s6, v98
	v_add_u32_e32 v100, s6, v99
	v_add_u32_e32 v101, s6, v100
	v_add_u32_e32 v102, s6, v101
	v_add_u32_e32 v103, s6, v102
	global_load_dwordx4 v[4:7], v96, s[64:65] nt
	global_load_dwordx4 v[8:11], v97, s[64:65] nt
	global_load_dwordx4 v[12:15], v98, s[64:65] nt
	global_load_dwordx4 v[16:19], v99, s[64:65] nt
	global_load_dwordx4 v[20:23], v100, s[64:65] nt
	global_load_dwordx4 v[24:27], v101, s[64:65] nt
	global_load_dwordx4 v[28:31], v102, s[64:65] nt
	global_load_dwordx4 v[32:35], v103, s[64:65] nt
	s_mov_b32 s72, 1
	s_add_u32 s52, s52, s94
	s_cmp_ge_u32 s52, s9
	s_cbranch_scc1 .Ldt7_procA
	s_cmpk_ge_u32 s52, 0x1410
	s_cbranch_scc1 .Ldt7_out1
	s_sub_i32 s0, s52, 0xa08
	s_mul_i32 s1, s0, 0xcc3
	s_lshr_b32 s1, s1, 20
	s_mul_i32 s2, s1, 0x141
	s_sub_u32 s2, s0, s2
	s_lshl_b32 s3, s2, 7
	s_mul_i32 s4, s1, 0x1410000
	s_add_u32 s3, s3, s4
	s_add_u32 s68, s54, s3
	s_addc_u32 s69, s55, 0
	s_mov_b32 s7, 0xa080
	s_lshl_b32 s4, s1, 10
	s_cmpk_lt_u32 s2, 0x80
	s_cbranch_scc1 .Ldt7_wlo1
	s_cmpk_eq_u32 s2, 0x80
	s_cbranch_scc1 .Ldt7_wlr1
	s_add_i32 s2, s2, -1

.Ldt7_ud1:
	v_mul_u32_u24_e32 v96, s7, v93
	s_lshl_b32 s6, s7, 6
	v_add_u32_e32 v96, v96, v94
	v_add_u32_e32 v97, s6, v96
	v_add_u32_e32 v98, s6, v97
	v_add_u32_e32 v99, s6, v98
	v_add_u32_e32 v100, s6, v99
	v_add_u32_e32 v101, s6, v100
	v_add_u32_e32 v102, s6, v101
	v_add_u32_e32 v103, s6, v102
	global_load_dwordx4 v[36:39], v96, s[68:69] nt
	global_load_dwordx4 v[40:43], v97, s[68:69] nt
	global_load_dwordx4 v[44:47], v98, s[68:69] nt
	global_load_dwordx4 v[48:51], v99, s[68:69] nt
	global_load_dwordx4 v[52:55], v100, s[68:69] nt
	global_load_dwordx4 v[56:59], v101, s[68:69] nt
	global_load_dwordx4 v[60:63], v102, s[68:69] nt
	global_load_dwordx4 v[64:67], v103, s[68:69] nt
	s_mov_b32 s73, 1
	s_add_u32 s52, s52, s94

.Ldt7_ud2:
	v_mul_u32_u24_e32 v96, s7, v93
	s_lshl_b32 s6, s7, 6
	v_add_u32_e32 v96, v96, v94
	v_add_u32_e32 v97, s6, v96
	v_add_u32_e32 v98, s6, v97
	v_add_u32_e32 v99, s6, v98
	v_add_u32_e32 v100, s6, v99
	v_add_u32_e32 v101, s6, v100
	v_add_u32_e32 v102, s6, v101
	v_add_u32_e32 v103, s6, v102
	global_load_dwordx4 v[4:7], v96, s[64:65] nt
	global_load_dwordx4 v[8:11], v97, s[64:65] nt
	global_load_dwordx4 v[12:15], v98, s[64:65] nt
	global_load_dwordx4 v[16:19], v99, s[64:65] nt
	global_load_dwordx4 v[20:23], v100, s[64:65] nt
	global_load_dwordx4 v[24:27], v101, s[64:65] nt
	global_load_dwordx4 v[28:31], v102, s[64:65] nt
	global_load_dwordx4 v[32:35], v103, s[64:65] nt
	s_mov_b32 s72, 1
	s_add_u32 s52, s52, s94

.Ldt8_nrot:
	s_addk_i32 s52, 0xa08
	s_mul_i32 s9, s94, 15
	s_add_u32 s52, s52, s9
	s_movk_i32 s9, 0x1c10
	s_cmp_ge_u32 s52, s9
	s_cbranch_scc1 .Ldt8_skip
	s_waitcnt lgkmcnt(0)
	s_barrier
	v_readlane_b32 s54, v254, 54
	v_readlane_b32 s55, v254, 55
	v_readlane_b32 s56, v253, 2
	v_readlane_b32 s57, v253, 3
	v_readlane_b32 s58, v253, 8
	v_readlane_b32 s59, v253, 9
	v_readlane_b32 s60, v253, 10
	v_readlane_b32 s61, v253, 11
	v_readlane_b32 s62, v254, 12
	v_readlane_b32 s63, v254, 13
	v_and_b32_e32 v106, 7, v180
	v_lshrrev_b32_e32 v93, 3, v180
	s_add_u32 s54, s54, 0xa080000
	s_addc_u32 s55, s55, 0
	s_add_u32 s58, s58, 0x5000000
	s_addc_u32 s59, s59, 0
	s_add_u32 s60, s60, 0x40000
	s_addc_u32 s61, s61, 0
	v_lshlrev_b32_e32 v94, 4, v106
	v_bfe_u32 v107, v180, 3, 1
	v_lshlrev_b32_e32 v108, 2, v106
	v_lshl_add_u32 v108, v107, 1, v108
	v_mul_u32_u24_e32 v84, 0x410, v108
	v_lshrrev_b32_e32 v109, 3, v93
	v_xor_b32_e32 v109, v109, v106
	v_lshlrev_b32_e32 v109, 3, v109
	v_and_b32_e32 v110, 6, v93
	v_or_b32_e32 v109, v109, v110
	v_lshl_add_u32 v84, v109, 1, v84
	v_cmp_ne_u32_e64 s[74:75], 0, v107
	v_mov_b32_e32 v104, 0x1000504
	v_mov_b32_e32 v105, 0x3020706
	v_mov_b32_e32 v111, 0x5040100
	v_mov_b32_e32 v112, 0x7060302
	v_cndmask_b32_e64 v104, v104, v111, s[74:75]
	v_cndmask_b32_e64 v105, v105, v112, s[74:75]
	v_lshrrev_b32_e32 v106, 6, v180
	v_and_b32_e32 v107, 63, v180
	v_lshrrev_b32_e32 v108, 2, v106
	v_add_u32_e32 v109, 0, v108
	v_xor_b32_e32 v109, v109, v107
	v_lshlrev_b32_e32 v109, 4, v109
	v_add_u32_e32 v110, 0, v106
	v_mul_u32_u24_e32 v110, 0x410, v110
	v_add_u32_e32 v85, v109, v110
	v_add_u32_e32 v109, 2, v108
	v_xor_b32_e32 v109, v109, v107
	v_lshlrev_b32_e32 v109, 4, v109
	v_add_u32_e32 v110, 8, v106
	v_mul_u32_u24_e32 v110, 0x410, v110
	v_add_u32_e32 v86, v109, v110
	v_add_u32_e32 v109, 4, v108
	v_xor_b32_e32 v109, v109, v107
	v_lshlrev_b32_e32 v109, 4, v109
	v_add_u32_e32 v110, 16, v106
	v_mul_u32_u24_e32 v110, 0x410, v110
	v_add_u32_e32 v87, v109, v110
	v_add_u32_e32 v109, 6, v108
	v_xor_b32_e32 v109, v109, v107
	v_lshlrev_b32_e32 v109, 4, v109
	v_add_u32_e32 v110, 24, v106
	v_mul_u32_u24_e32 v110, 0x410, v110
	v_add_u32_e32 v88, v109, v110
	v_lshlrev_b32_e32 v109, 13, v106
	v_lshl_add_u32 v89, v107, 4, v109
	v_add_u32_e32 v90, 0x10000, v89
	v_add_u32_e32 v91, 0x20000, v89
	v_add_u32_e32 v92, 0x30000, v89
	s_mov_b32 s53, 0
	s_mov_b32 s73, 0
	s_cmpk_ge_u32 s52, 0x1410
	s_cbranch_scc1 .Ldt8_out0
	s_sub_i32 s0, s52, 0xa08
	s_mul_i32 s1, s0, 0xcc3
	s_lshr_b32 s1, s1, 20
	s_mul_i32 s2, s1, 0x141
	s_sub_u32 s2, s0, s2
	s_lshl_b32 s3, s2, 7
	s_mul_i32 s4, s1, 0x1410000
	s_add_u32 s3, s3, s4
	s_add_u32 s64, s54, s3
	s_addc_u32 s65, s55, 0
	s_mov_b32 s7, 0xa080
	s_lshl_b32 s4, s1, 10
	s_cmpk_lt_u32 s2, 0x80
	s_cbranch_scc1 .Ldt8_wlo0
	s_cmpk_eq_u32 s2, 0x80
	s_cbranch_scc1 .Ldt8_wlr0
	s_add_i32 s2, s2, -1

.Ldt8_end:
	s_nop 1
	s_waitcnt lgkmcnt(0)
	s_barrier
.Ldt8_skip:
	s_waitcnt vmcnt(0)
	s_barrier
	s_mov_b64 s[0:1], exec
	v_readlane_b32 s2, v254, 9
	v_readlane_b32 s3, v254, 10
	s_and_b64 s[2:3], s[0:1], s[2:3]
	s_mov_b64 exec, s[2:3]
	s_cbranch_execz .LBB0_868
	s_add_i32 s2, 0, 0x20000
	v_mov_b32_e32 v0, s2
	s_waitcnt vmcnt(0) expcnt(0) lgkmcnt(0)
	ds_read_b32 v2, v0
	s_add_i32 s2, 0, 0x20004
	v_mov_b32_e32 v0, s2
	ds_read_b32 v0, v0
	s_waitcnt lgkmcnt(1)
	v_cmp_ne_u32_e32 vcc, 0, v2
	s_cbranch_vccnz .LBB0_832
	v_readlane_b32 s4, v254, 0
	v_readlane_b32 s2, v254, 8
	v_readlane_b32 s8, v254, 4
	s_mul_i32 s16, s95, s2
	v_readlane_b32 s9, v254, 5
	s_add_u32 s2, s8, 0x1000
	s_addc_u32 s3, s9, 0
	v_readlane_b32 s5, v254, 1
	s_add_u32 s4, s8, 0x1100
	v_readlane_b32 s6, v254, 2
	s_addc_u32 s5, s9, 0
	v_readlane_b32 s7, v254, 3
	s_add_u32 s6, s8, 0x1200
	s_addc_u32 s7, s9, 0
	s_add_u32 s8, s8, 0x1300
	s_mul_i32 s16, s16, s94
	s_addc_u32 s9, s9, 0
	s_mov_b32 s17, 1
	v_mov_b32_e32 v16, 0
	v_readlane_b32 s10, v254, 6
	v_readlane_b32 s11, v254, 7
	s_branch .LBB0_820
